# hand-written G1 epilogue now dispatched (group-order flag polarity fixed): one scalar dispatch per unit, QK-norm gains waited once; plus C=0 peel, SGPR DMA addressing, no setprio flips
# speedup vs baseline: 1.0250x; 1.0098x over previous
; #define SW_BEGIN(id) unsigned long long sw_t0_##id = 0; if (SW_ID == (id)) sw_t0_##id = __builtin_amdgcn_s_memrealtime()
; #define SW_END(id) do { if (SW_ID == (id)) sw_acc += __builtin_amdgcn_s_memrealtime() - sw_t0_##id; } while (0)
; #define SW_BEGIN(id) do {} while (0)
; #define SW_END(id) do {} while (0)
;     __device__ __forceinline__ void operator()(const f32x4 (&acc)[2][2][4][2], const Unit& u, int wr, int wc, int fr, int fq) const {
;         const int sec = u.pn >> 1;
;         const int row0 = u.pm * BM + wr * 64 + fr;
;         const int cs = (u.pn & 1) * BM + wc * 64 + 8 * fq;
;         const bool isqg = (sec == 0) || (sec == 3) || (sec == 4) || (sec == 7);
;         const int dsec = isqg ? ((sec == 0) ? S_SBQ : (sec == 3) ? S_SBG : (sec == 4) ? S_DAQ : S_DAG) : ((sec == 1) ? 0 : (sec == 2) ? 1 : (sec == 5) ? 2 : 3);
;         const int bjstep = isqg ? 1024 : 32;
; template <class Epi>
; __device__ __forceinline__ void gemm_phase(LAS unsigned char* lds, const Gemm g, const StaticOrder& S, const Epi& E, unsigned long long& sw_acc) {
;     ...
;         { SW_BEGIN(20); E(acc, cur, wr, wc, fr, fq); SW_END(20); }
.LBB0_137:
	s_and_b64 vcc, exec, s[84:85]
	s_cbranch_vccnz .Lepi_orig_g1
	s_lshr_b32 s57, s69, 1
	s_cmp_eq_u32 s57, 0
	s_cbranch_scc1 .Lepi_qs
	s_cmp_eq_u32 s57, 1
	s_cbranch_scc1 .Lepi_kvp
	s_cmp_eq_u32 s57, 2
	s_cbranch_scc1 .Lepi_kvp
	s_cmp_eq_u32 s57, 3
	s_cbranch_scc1 .Lepi_silu
	s_cmp_eq_u32 s57, 4
	s_cbranch_scc1 .Lepi_qn
	s_cmp_eq_u32 s57, 5
	s_cbranch_scc1 .Lepi_kn
	s_cmp_eq_u32 s57, 6
	s_cbranch_scc1 .Lepi_kvp
	s_cmp_eq_u32 s57, 7
	s_cbranch_scc1 .Lepi_silu
